# prologue: once-read f32 weights and x rows loaded non-temporally
# speedup vs baseline: 1.0038x; 1.0038x over previous
.LBB11_52:
	v_mov_b64_e32 v[34:35], v[30:31]
	v_mov_b64_e32 v[38:39], v[26:27]
	v_mov_b64_e32 v[42:43], v[22:23]
	v_mov_b64_e32 v[46:47], v[18:19]
	v_mov_b64_e32 v[50:51], v[14:15]
	v_mov_b64_e32 v[54:55], v[10:11]
	v_mov_b64_e32 v[58:59], v[6:7]
	v_mov_b64_e32 v[62:63], v[2:3]
	s_xor_b64 s[26:27], s[24:25], -1
	s_andn2_b64 vcc, exec, s[24:25]
	v_mov_b64_e32 v[32:33], v[28:29]
	v_mov_b64_e32 v[36:37], v[24:25]
	v_mov_b64_e32 v[40:41], v[20:21]
	v_mov_b64_e32 v[44:45], v[16:17]
	v_mov_b64_e32 v[48:49], v[12:13]
	v_mov_b64_e32 v[52:53], v[8:9]
	s_mov_b32 s31, s20
	s_mov_b32 s24, s69
	v_mov_b32_e32 v81, v69
	v_mov_b64_e32 v[74:75], v[70:71]
	v_mov_b64_e32 v[56:57], v[4:5]
	v_mov_b64_e32 v[60:61], v[0:1]
	s_cbranch_vccnz .LBB11_59
	s_lshr_b32 s21, s34, 5
	v_cvt_f32_u32_e32 v32, s21
	s_sub_i32 s28, 0, s21
	s_abs_i32 s25, s68
	s_ashr_i32 s24, s68, 31
	v_rcp_iflag_f32_e32 v32, v32
	s_nop 0
	v_mul_f32_e32 v32, 0x4f7ffffe, v32
	v_cvt_u32_f32_e32 v32, v32
	s_nop 0
	v_readfirstlane_b32 s29, v32
	s_mul_i32 s28, s28, s29
	s_mul_hi_u32 s28, s29, s28
	s_add_i32 s29, s29, s28
	s_mul_hi_u32 s28, s25, s29
	s_mul_i32 s29, s28, s21
	s_sub_i32 s25, s25, s29
	s_add_i32 s31, s28, 1
	s_sub_i32 s29, s25, s21
	s_cmp_ge_u32 s25, s21
	s_cselect_b32 s28, s31, s28
	s_cselect_b32 s25, s29, s25
	s_add_i32 s29, s28, 1
	s_cmp_ge_u32 s25, s21
	s_cselect_b32 s25, s29, s28
	s_xor_b32 s25, s25, s24
	s_sub_i32 s24, s25, s24
	s_lshl_b32 s31, s24, 6
	v_add_u32_e32 v74, s31, v65
	v_add_u32_e32 v40, 16, v74
	v_add_u32_e32 v48, 32, v74
	v_add_u32_e32 v56, 48, v74
	v_mad_u64_u32 v[32:33], s[28:29], v74, s35, 0
	v_ashrrev_i32_e32 v43, 31, v40
	v_mad_u64_u32 v[40:41], s[36:37], v40, s35, 0
	v_ashrrev_i32_e32 v51, 31, v48
	v_mad_u64_u32 v[48:49], s[36:37], v48, s35, 0
	v_ashrrev_i32_e32 v59, 31, v56
	v_mad_u64_u32 v[56:57], s[36:37], v56, s35, 0
	v_ashrrev_i32_e32 v75, 31, v74
	v_mov_b32_e32 v34, v33
	v_mov_b32_e32 v42, v41
	v_mov_b32_e32 v50, v49
	v_mov_b32_e32 v58, v57
	v_mad_u64_u32 v[34:35], s[28:29], v75, s35, v[34:35]
	v_mad_u64_u32 v[42:43], s[36:37], v43, s35, v[42:43]
	v_mad_u64_u32 v[50:51], s[36:37], v51, s35, v[50:51]
	v_mad_u64_u32 v[58:59], s[36:37], v59, s35, v[58:59]
	v_mov_b32_e32 v33, v34
	v_add_u32_e32 v34, 8, v74
	v_mov_b32_e32 v41, v42
	v_add_u32_e32 v42, 24, v74
	v_mov_b32_e32 v49, v50
	v_add_u32_e32 v50, 40, v74
	v_mov_b32_e32 v57, v58
	v_add_u32_e32 v58, 56, v74
	s_mul_i32 s21, s24, s21
	v_ashrrev_i32_e32 v37, 31, v34
	v_mad_u64_u32 v[34:35], s[36:37], v34, s35, 0
	v_ashrrev_i32_e32 v45, 31, v42
	v_mad_u64_u32 v[42:43], s[36:37], v42, s35, 0
	v_ashrrev_i32_e32 v53, 31, v50
	v_mad_u64_u32 v[50:51], s[36:37], v50, s35, 0
	v_ashrrev_i32_e32 v61, 31, v58
	v_mad_u64_u32 v[58:59], s[36:37], v58, s35, 0
	s_sub_i32 s21, s68, s21
	v_mov_b32_e32 v36, v35
	v_mov_b32_e32 v44, v43
	v_mov_b32_e32 v52, v51
	v_mov_b32_e32 v60, v59
	s_lshl_b32 s24, s21, 5
	v_mad_u64_u32 v[36:37], s[36:37], v37, s35, v[36:37]
	v_mad_u64_u32 v[44:45], s[36:37], v45, s35, v[44:45]
	v_mad_u64_u32 v[52:53], s[36:37], v53, s35, v[52:53]
	v_mad_u64_u32 v[60:61], s[36:37], v61, s35, v[60:61]
	s_ashr_i32 s25, s24, 31
	v_mov_b32_e32 v35, v36
	v_mov_b32_e32 v43, v44
	v_mov_b32_e32 v51, v52
	v_mov_b32_e32 v59, v60
	v_lshl_add_u64 v[32:33], v[32:33], 2, s[10:11]
	s_lshl_b64 s[28:29], s[24:25], 2
	v_lshl_add_u64 v[34:35], v[34:35], 2, s[10:11]
	v_lshl_add_u64 v[40:41], v[40:41], 2, s[10:11]
	v_lshl_add_u64 v[42:43], v[42:43], 2, s[10:11]
	v_lshl_add_u64 v[48:49], v[48:49], 2, s[10:11]
	v_lshl_add_u64 v[50:51], v[50:51], 2, s[10:11]
	v_lshl_add_u64 v[56:57], v[56:57], 2, s[10:11]
	v_lshl_add_u64 v[58:59], v[58:59], 2, s[10:11]
	v_lshl_add_u64 v[32:33], v[32:33], 0, s[28:29]
	v_lshl_add_u64 v[34:35], v[34:35], 0, s[28:29]
	v_lshl_add_u64 v[40:41], v[40:41], 0, s[28:29]
	v_lshl_add_u64 v[42:43], v[42:43], 0, s[28:29]
	v_lshl_add_u64 v[48:49], v[48:49], 0, s[28:29]
	v_lshl_add_u64 v[50:51], v[50:51], 0, s[28:29]
	v_lshl_add_u64 v[56:57], v[56:57], 0, s[28:29]
	v_lshl_add_u64 v[58:59], v[58:59], 0, s[28:29]
	v_lshl_add_u64 v[32:33], v[32:33], 0, v[66:67]
	v_lshl_add_u64 v[36:37], v[34:35], 0, v[66:67]
	v_lshl_add_u64 v[40:41], v[40:41], 0, v[66:67]
	v_lshl_add_u64 v[44:45], v[42:43], 0, v[66:67]
	v_lshl_add_u64 v[48:49], v[48:49], 0, v[66:67]
	v_lshl_add_u64 v[52:53], v[50:51], 0, v[66:67]
	v_lshl_add_u64 v[56:57], v[56:57], 0, v[66:67]
	v_lshl_add_u64 v[60:61], v[58:59], 0, v[66:67]
	global_load_dwordx4 v[32:35], v[32:33], off nt
	s_nop 0
	global_load_dwordx4 v[36:39], v[36:37], off nt
	s_nop 0
	global_load_dwordx4 v[40:43], v[40:41], off nt
	s_nop 0
	global_load_dwordx4 v[44:47], v[44:45], off nt
	s_nop 0
	global_load_dwordx4 v[48:51], v[48:49], off nt
	s_nop 0
	global_load_dwordx4 v[52:55], v[52:53], off nt
	s_nop 0
	global_load_dwordx4 v[56:59], v[56:57], off nt
	s_nop 0
	global_load_dwordx4 v[60:63], v[60:61], off nt
	s_cmp_eq_u64 s[8:9], 0
	s_cbranch_scc1 .LBB11_55
	v_lshl_add_u64 v[74:75], v[74:75], 2, s[8:9]
	global_load_dword v82, v[74:75], off
	global_load_dword v84, v[74:75], off offset:32
	global_load_dword v86, v[74:75], off offset:64
	global_load_dword v88, v[74:75], off offset:96
	global_load_dword v90, v[74:75], off offset:128
	global_load_dword v92, v[74:75], off offset:160
	global_load_dword v94, v[74:75], off offset:192
	s_nop 0
	global_load_dword v74, v[74:75], off offset:224
	s_waitcnt vmcnt(7)
	v_pk_mul_f32 v[34:35], v[34:35], v[82:83] op_sel_hi:[1,0]
	v_pk_mul_f32 v[32:33], v[32:33], v[82:83] op_sel_hi:[1,0]
	s_waitcnt vmcnt(6)
	v_pk_mul_f32 v[38:39], v[38:39], v[84:85] op_sel_hi:[1,0]
	v_pk_mul_f32 v[36:37], v[36:37], v[84:85] op_sel_hi:[1,0]
	s_waitcnt vmcnt(5)
	v_pk_mul_f32 v[42:43], v[42:43], v[86:87] op_sel_hi:[1,0]
	v_pk_mul_f32 v[40:41], v[40:41], v[86:87] op_sel_hi:[1,0]
	s_waitcnt vmcnt(4)
	v_pk_mul_f32 v[46:47], v[46:47], v[88:89] op_sel_hi:[1,0]
	v_pk_mul_f32 v[44:45], v[44:45], v[88:89] op_sel_hi:[1,0]
	s_waitcnt vmcnt(3)
	v_pk_mul_f32 v[50:51], v[50:51], v[90:91] op_sel_hi:[1,0]
	v_pk_mul_f32 v[48:49], v[48:49], v[90:91] op_sel_hi:[1,0]
	s_waitcnt vmcnt(2)
	v_pk_mul_f32 v[54:55], v[54:55], v[92:93] op_sel_hi:[1,0]
	v_pk_mul_f32 v[52:53], v[52:53], v[92:93] op_sel_hi:[1,0]
	s_waitcnt vmcnt(1)
	v_pk_mul_f32 v[58:59], v[58:59], v[94:95] op_sel_hi:[1,0]
	v_pk_mul_f32 v[56:57], v[56:57], v[94:95] op_sel_hi:[1,0]
	s_waitcnt vmcnt(0)
	v_pk_mul_f32 v[62:63], v[62:63], v[74:75] op_sel_hi:[1,0]
	v_pk_mul_f32 v[60:61], v[60:61], v[74:75] op_sel_hi:[1,0]

.LBB11_70:
	s_cmp_lg_u64 s[28:29], 0
	v_mov_b32_e32 v0, 0
	s_cselect_b64 s[26:27], -1, 0
	s_cmp_eq_u64 s[28:29], 0
	v_lshl_add_u64 v[10:11], v[64:65], 2, s[28:29]
	v_mov_b32_e32 v2, 0
	v_mov_b32_e32 v3, 0
	v_mov_b32_e32 v4, 0
	v_mov_b32_e32 v5, 0
	s_cbranch_scc1 .LBB11_72
	global_load_dwordx4 v[2:5], v[10:11], off nt
.LBB11_72:
	s_waitcnt vmcnt(0)
	v_cvt_pk_bf16_f32 v26, v2, v3
	v_cvt_pk_bf16_f32 v27, v4, v5
	s_andn2_b64 vcc, exec, s[26:27]
	v_lshlrev_b32_e32 v12, 16, v27
	v_lshlrev_b32_e32 v8, 16, v26
	v_and_b32_e32 v9, 0xffff0000, v26
	v_and_b32_e32 v13, 0xffff0000, v27
	v_sub_f32_e32 v1, v4, v12
	v_sub_f32_e32 v4, v5, v13
	v_sub_f32_e32 v2, v2, v8
	v_sub_f32_e32 v3, v3, v9
	v_cvt_pk_bf16_f32 v28, v2, v3
	v_cvt_pk_bf16_f32 v29, v1, v4
	v_cndmask_b32_e64 v1, 0, 1, s[26:27]
	v_cmp_ne_u32_e64 s[8:9], 1, v1
	v_mov_b32_e32 v1, 0
	v_mov_b32_e32 v2, 0
	v_mov_b32_e32 v3, 0
	s_cbranch_vccnz .LBB11_74
	global_load_dwordx4 v[0:3], v[10:11], off offset:1024 nt
.LBB11_74:
	s_waitcnt vmcnt(0)
	v_cvt_pk_bf16_f32 v18, v0, v1
	v_cvt_pk_bf16_f32 v19, v2, v3
	v_mov_b32_e32 v4, 0
	v_lshlrev_b32_e32 v30, 16, v18
	v_and_b32_e32 v31, 0xffff0000, v18
	v_lshlrev_b32_e32 v32, 16, v19
	v_and_b32_e32 v33, 0xffff0000, v19
	v_sub_f32_e32 v2, v2, v32
	v_sub_f32_e32 v3, v3, v33
	v_sub_f32_e32 v0, v0, v30
	v_sub_f32_e32 v1, v1, v31
	v_cvt_pk_bf16_f32 v20, v0, v1
	v_cvt_pk_bf16_f32 v21, v2, v3
	s_and_b64 vcc, exec, s[8:9]
	v_mov_b32_e32 v0, 0
	v_mov_b32_e32 v1, 0
	v_mov_b32_e32 v2, 0
	v_mov_b32_e32 v3, 0
	s_cbranch_vccnz .LBB11_76
	global_load_dwordx4 v[0:3], v[10:11], off offset:2048 nt
.LBB11_76:
	s_waitcnt vmcnt(0)
	v_cvt_pk_bf16_f32 v22, v0, v1
	v_cvt_pk_bf16_f32 v23, v2, v3
	s_and_b64 vcc, exec, s[8:9]
	v_lshlrev_b32_e32 v34, 16, v22
	v_and_b32_e32 v35, 0xffff0000, v22
	v_lshlrev_b32_e32 v36, 16, v23
	s_waitcnt lgkmcnt(0)
	v_and_b32_e32 v37, 0xffff0000, v23
	v_mov_b32_e32 v5, 0
	v_mov_b32_e32 v6, 0
	v_mov_b32_e32 v7, 0
	v_sub_f32_e32 v2, v2, v36
	v_sub_f32_e32 v3, v3, v37
	v_sub_f32_e32 v0, v0, v34
	v_sub_f32_e32 v1, v1, v35
	v_cvt_pk_bf16_f32 v24, v0, v1
	v_cvt_pk_bf16_f32 v25, v2, v3
	s_cbranch_vccnz .LBB11_78
	global_load_dwordx4 v[4:7], v[10:11], off offset:3072 nt
